# RG-LRU tile alternation across the two waves of a SIMD: state handed over through an LDS word + sequence flag (polling) instead of barriers, so consecutive tiles' gate math overlaps
# baseline (speedup 1.0000x reference)
; __device__ __forceinline__ float log1p_small(float e) { return e < 0.03f ? e * (1.f - e * (0.5f - e * (0.33333334f - 0.25f * e))) : __logf(1.f + e); }
; template <int DIR>
; __device__ __forceinline__ void lru_item(const Params& p, int item, int lane) {
;     const int db = item & 3, blk = (item >> 2) & 7, bl = item >> 5;
;     const int r = lane & 31, h = lane >> 5;
;     const int dl = db * 32 + r, d = blk * 128 + dl;
;     const bf16_t* WGt = (const bf16_t*)(p.ws + OFF_WG);
;     const bf16_t* wa = WGt + ((size_t)((DIR * 8 + blk) * 2 + 0) * 128 + dl) * 128 + 8 * h;
;     const bf16_t* wi = WGt + ((size_t)((DIR * 8 + blk) * 2 + 1) * 128 + dl) * 128 + 8 * h;
;     bf16x8 Wa[8], Wi[8];
; #pragma unroll
;     for (int s = 0; s < 8; ++s) { Wa[s] = ld8(wa + 16 * s); Wi[s] = ld8(wi + 16 * s); }
;     bf16x8 I0, I1;
; #pragma unroll
;     for (int e = 0; e < 8; ++e) { I0[e] = (16 * (2 * db) + 8 * h + e == dl) ? (short)0x3F80 : (short)0; I1[e] = (16 * (2 * db + 1) + 8 * h + e == dl) ? (short)0x3F80 : (short)0; }
;     const float ba = p.lru_ba[DIR * 1024 + d], bi = p.lru_bi[DIR * 1024 + d];
;     const float c8 = -8.f * log1p_small(__expf(-p.lru_lambda[DIR * 1024 + d]));
;     const bf16_t* uu = (const bf16_t*)(p.ws + OFF_U);
;     bf16_t* yl = (bf16_t*)(p.ws + (DIR ? OFF_YLB : OFF_YLF));
;     float hst = 0.f;
;     auto tile_row0 = [&](int t) -> size_t { const bool cx = t < 8; const int tl = cx ? (DIR ? 7 - t : t) : (DIR ? 71 - t : t - 8);
;         return cx ? (size_t)bl * 256 + tl * 32 : (size_t)CGR + (size_t)bl * 2048 + tl * 32; };
;     bf16x8 uf[8], ui0, ui1;
;     { const bf16_t* up = uu + (tile_row0(0) + r) * 1024 + blk * 128 + 8 * h;
; #pragma unroll
;       for (int s = 0; s < 8; ++s) uf[s] = ld8(up + 16 * s);
;       ui0 = ld8(up + 32 * db); ui1 = ld8(up + 32 * db + 16); }
; __global__ void __launch_bounds__(512) mega(Params p_arg) {
;     ...
;             int l2; asm volatile("v_mbcnt_lo_u32_b32 %0, -1, 0\n\tv_mbcnt_hi_u32_b32 %0, -1, %0" : "=v"(l2));
;             int t2 = wv_ * 64 + l2;
;             const int wid2 = wv_, lane2 = t2 & 63;
;             if (wid2 < 4) for (int cu = wg; cu < BG * 8 * 2; cu += G) { const int it = (cu >> 1) * 4 + wid2; if (cu & 1) lru_item<1>(p, it, lane2); else lru_item<0>(p, it, lane2); }
.LBB0_471:
	v_readlane_b32 s2, v255, 51
	s_lshr_b32 s101, s93, 2
	s_and_b32 s93, s93, 3
	s_cmp_gt_i32 s93, 3
	v_readlane_b32 s3, v255, 52
	s_cselect_b64 s[0:1], -1, 0
	s_xor_b64 s[2:3], s[2:3], -1
	s_or_b64 s[0:1], s[0:1], s[2:3]
	v_readlane_b32 s86, v255, 9
	v_readlane_b32 s84, v255, 14
	v_readlane_b32 s72, v255, 16
	v_readlane_b32 s38, v255, 49
	v_readlane_b32 s44, v255, 47
	v_readlane_b32 s60, v255, 45
	v_readlane_b32 s24, v255, 40
	v_readlane_b32 s28, v255, 36
	s_and_b64 vcc, exec, s[0:1]
	v_readlane_b32 s88, v255, 18
	v_readlane_b32 s87, v255, 10
	v_readlane_b32 s91, v255, 11
	v_readlane_b32 s23, v255, 4
	v_readlane_b32 s85, v255, 15
	v_readlane_b32 s73, v255, 17
	s_mov_b32 s89, 0x7900000
	s_mov_b32 s63, 0x40000
	s_mov_b64 s[64:65], 0x48000
	s_mov_b32 s55, 0x50000
	s_mov_b32 s62, 0x3cf5c28f
	s_mov_b32 s56, 0x800000
	s_mov_b32 s58, 0x3f317217
	s_mov_b32 s59, 0x7f800000
	s_movk_i32 s78, 0x2a00
	v_readlane_b32 s39, v255, 50
	v_readlane_b32 s45, v255, 48
	v_readlane_b32 s61, v255, 46
	v_readlane_b32 s79, v255, 35
	v_readlane_b32 s76, v255, 44
	v_readlane_b32 s26, v255, 42
	v_readlane_b32 s25, v255, 41
	v_readlane_b32 s29, v255, 37
	v_readlane_b32 s30, v255, 38
	v_readlane_b32 s31, v255, 39
	v_mbcnt_lo_u32_b32 v0, -1, 0
	v_mbcnt_hi_u32_b32 v0, -1, v0
	v_readlane_b32 s27, v255, 43
	s_cbranch_vccnz .LBB0_497
	v_lshlrev_b32_e32 v188, 2, v0
	s_lshl_b32 s100, s93, 8
	v_add_u32_e32 v188, s100, v188
	v_add_u32_e32 v188, 0x26000, v188
	ds_write_b32 v188, v193
	s_lshl_b32 s100, s93, 2
	v_mov_b32_e32 v189, s100
	v_add_u32_e32 v189, 0x26400, v189
	ds_write_b32 v189, v193
	s_waitcnt lgkmcnt(0)
	s_barrier
	v_bfe_u32 v2, v0, 5, 1
	s_lshl_b32 s0, s93, 5
	s_and_b32 s4, s0, 0x60
	v_lshlrev_b32_e32 v162, 3, v2
	v_and_b32_e32 v160, 31, v0
	v_or_b32_e32 v4, s4, v162
	v_or_b32_e32 v163, s4, v160
	v_cmp_eq_u32_e32 vcc, v162, v160
	v_mov_b32_e32 v20, 0x3f80
	v_or_b32_e32 v6, 16, v4
	v_cndmask_b32_e32 v5, 0, v20, vcc
	v_cmp_eq_u32_e32 vcc, v6, v163
	v_or_b32_e32 v8, 1, v4
	v_or_b32_e32 v7, 2, v4
	v_cndmask_b32_e32 v6, 0, v20, vcc
	v_cmp_eq_u32_e32 vcc, v8, v163
	v_or_b32_e32 v10, 17, v4
	v_or_b32_e32 v9, 18, v4
	v_cndmask_b32_e32 v8, 0, v20, vcc
	v_cmp_eq_u32_e32 vcc, v7, v163
	v_or_b32_e32 v12, 3, v4
	v_or_b32_e32 v11, 4, v4
	v_cndmask_b32_e32 v7, 0, v20, vcc
	v_cmp_eq_u32_e32 vcc, v10, v163
	v_or_b32_e32 v14, 19, v4
	v_or_b32_e32 v13, 20, v4
	v_cndmask_b32_e32 v10, 0, v20, vcc
	v_cmp_eq_u32_e32 vcc, v9, v163
	v_or_b32_e32 v16, 5, v4
	v_or_b32_e32 v15, 6, v4
	v_cndmask_b32_e32 v9, 0, v20, vcc
	v_cmp_eq_u32_e32 vcc, v12, v163
	v_or_b32_e32 v18, 21, v4
	s_add_u32 s0, s94, 0x2d80000
	v_cndmask_b32_e32 v12, 0, v20, vcc
	v_cmp_eq_u32_e32 vcc, v11, v163
	v_or_b32_e32 v17, 22, v4
	s_addc_u32 s1, s95, 0
	v_cndmask_b32_e32 v11, 0, v20, vcc
	v_cmp_eq_u32_e32 vcc, v14, v163
	v_or_b32_e32 v19, 7, v4
	v_or_b32_e32 v4, 23, v4
	v_cndmask_b32_e32 v14, 0, v20, vcc
	v_cmp_eq_u32_e32 vcc, v13, v163
	s_add_u32 s6, s94, 0x36100000
	v_and_b32_e32 v1, 63, v0
	v_cndmask_b32_e32 v13, 0, v20, vcc
	v_cmp_eq_u32_e32 vcc, v16, v163
	s_addc_u32 s7, s95, 0
	v_lshlrev_b32_e32 v192, 4, v2
	v_cndmask_b32_e32 v16, 0, v20, vcc
	v_cmp_eq_u32_e32 vcc, v15, v163
	v_lshlrev_b32_e32 v0, 8, v0
	v_lshlrev_b32_e32 v3, 7, v163
	v_cndmask_b32_e32 v15, 0, v20, vcc
	v_cmp_eq_u32_e32 vcc, v18, v163
	s_mov_b32 s2, 0x5040100
	v_lshl_add_u64 v[164:165], s[6:7], 0, v[192:193]
	v_cndmask_b32_e32 v18, 0, v20, vcc
	v_cmp_eq_u32_e32 vcc, v17, v163
	v_lshlrev_b32_e32 v2, 2, v1
	v_and_b32_e32 v192, 0x2000, v0
	v_cndmask_b32_e32 v17, 0, v20, vcc
	v_cmp_eq_u32_e32 vcc, v19, v163
	v_mov_b32_e32 v161, v193
	v_perm_b32 v50, v16, v11, s2
	v_cndmask_b32_e32 v19, 0, v20, vcc
	v_cmp_eq_u32_e32 vcc, v4, v163
	v_perm_b32 v51, v19, v15, s2
	v_perm_b32 v49, v12, v7, s2
	v_cndmask_b32_e32 v4, 0, v20, vcc
	v_perm_b32 v48, v8, v5, s2
	v_perm_b32 v55, v4, v17, s2
	v_perm_b32 v54, v18, v13, s2
	v_perm_b32 v53, v14, v9, s2
	v_perm_b32 v52, v10, v6, s2
	v_xor_b32_e32 v180, 0x80, v2
	v_cmp_gt_u32_e64 s[2:3], 32, v1
	v_lshl_add_u64 v[166:167], s[94:95], 0, v[192:193]
	s_lshl_b32 s16, s92, 1
	v_lshlrev_b32_e32 v181, 1, v3
	s_lshl_b32 s66, s4, 1
	s_mov_b32 s17, s92
	s_branch .LBB0_474

; __device__ __forceinline__ float log1p_small(float e) { return e < 0.03f ? e * (1.f - e * (0.5f - e * (0.33333334f - 0.25f * e))) : __logf(1.f + e); }
; __device__ __forceinline__ f32x16 mfma32(bf16x8 a, bf16x8 b, f32x16 c) { return __builtin_amdgcn_mfma_f32_32x32x16_bf16(a, b, c, 0, 0, 0); }
; template <int DIR>
; __device__ __forceinline__ void lru_item(const Params& p, int item, int lane) {
;     ...
;     const float c8 = -8.f * log1p_small(__expf(-p.lru_lambda[DIR * 1024 + d]));
;     const bf16_t* uu = (const bf16_t*)(p.ws + OFF_U);
;     bf16_t* yl = (bf16_t*)(p.ws + (DIR ? OFF_YLB : OFF_YLF));
;     float hst = 0.f;
;     auto tile_row0 = [&](int t) -> size_t { const bool cx = t < 8; const int tl = cx ? (DIR ? 7 - t : t) : (DIR ? 71 - t : t - 8);
;         return cx ? (size_t)bl * 256 + tl * 32 : (size_t)CGR + (size_t)bl * 2048 + tl * 32; };
;     bf16x8 uf[8], ui0, ui1;
;     { const bf16_t* up = uu + (tile_row0(0) + r) * 1024 + blk * 128 + 8 * h;
; #pragma unroll
;       for (int s = 0; s < 8; ++s) uf[s] = ld8(up + 16 * s);
;       ui0 = ld8(up + 32 * db); ui1 = ld8(up + 32 * db + 16); }
; #pragma unroll 1
;     for (int t = 0; t < 72; ++t) {
;         const bool is_ctx = t < 8;
;         const int tile = is_ctx ? (DIR ? 7 - t : t) : (DIR ? 71 - t : t - 8);
;         f32x16 Aa, Ai, Au;
; #pragma unroll
;         for (int e = 0; e < 16; ++e) { Aa[e] = 0.f; Ai[e] = 0.f; Au[e] = 0.f; }
; #pragma unroll
;         for (int s = 0; s < 8; ++s) { Aa = mfma32(uf[s], Wa[s], Aa); Ai = mfma32(uf[s], Wi[s], Ai); }
;         Au = mfma32(ui0, I0, Au); Au = mfma32(ui1, I1, Au);
;         { const int tn = t + 1 < 72 ? t + 1 : 71; const bf16_t* up = uu + (tile_row0(tn) + r) * 1024 + blk * 128 + 8 * h;
; #pragma unroll
;           for (int s = 0; s < 8; ++s) uf[s] = ld8(up + 16 * s);
;           ui0 = ld8(up + 32 * db); ui1 = ld8(up + 32 * db + 16); }
.LBB0_477:
	s_andn2_saveexec_b64 s[4:5], s[8:9]
	v_fmamk_f32 v0, v1, 0xbe800000, v237
	v_fma_f32 v0, -v1, v0, 0.5
	v_fma_f32 v0, -v1, v0, 1.0
	v_mul_f32_e32 v0, v1, v0
	s_or_b64 exec, exec, s[4:5]
	s_ashr_i32 s8, s11, 5
	s_ashr_i32 s9, s8, 31
	s_lshl_b64 s[4:5], s[8:9], 8
	v_mov_b32_e32 v3, s5
	v_or_b32_e32 v2, s4, v160
	v_lshlrev_b64 v[2:3], 11, v[2:3]
	v_lshl_add_u64 v[2:3], s[6:7], 0, v[2:3]
	s_lshl_b32 s14, s10, 1
	s_mov_b32 s15, s67
	v_lshl_add_u64 v[2:3], v[2:3], 0, s[14:15]
	v_lshl_add_u64 v[2:3], v[2:3], 0, v[192:193]
	s_lshl_b32 s12, s101, 16
	s_sub_u32 s12, 0x70000, s12
	s_mov_b32 s13, 0
	v_lshl_add_u64 v[4:5], v[2:3], 0, s[12:13]
	s_lshl_b32 s12, s101, 16
	s_sub_u32 s12, 0x70000, s12
	v_add_co_u32_e32 v2, vcc, s12, v2
	v_lshl_add_u64 v[174:175], v[164:165], 0, s[14:15]
	s_nop 0
	v_addc_co_u32_e32 v3, vcc, 0, v3, vcc
	global_load_dwordx4 v[148:151], v[4:5], off offset:32
	global_load_dwordx4 v[144:147], v[4:5], off offset:64
	global_load_dwordx4 v[140:143], v[4:5], off offset:96
	global_load_dwordx4 v[136:139], v[4:5], off offset:128
	global_load_dwordx4 v[132:135], v[4:5], off offset:160
	global_load_dwordx4 v[128:131], v[4:5], off offset:192
	global_load_dwordx4 v[156:159], v[2:3], off
	global_load_dwordx4 v[124:127], v[4:5], off offset:224
	v_lshl_add_u64 v[2:3], v[4:5], 0, s[66:67]
	global_load_dwordx4 v[152:155], v[2:3], off
	global_load_dwordx4 v[120:123], v[2:3], off offset:32
	s_lshl_b64 s[14:15], s[8:9], 11
	s_add_u32 s13, s14, 0x1000
	v_mul_f32_e32 v0, 0xc1000000, v0
	s_addc_u32 s14, s15, 0
	s_lshl_b64 s[8:9], s[8:9], 22
	v_mul_f32_e32 v176, 0x3fb8aa3b, v0
	v_mov_b32_e32 v1, s9
	v_or_b32_e32 v0, s8, v182
	s_mov_b32 s12, s101
	v_mov_b32_e32 v171, v170
	v_mov_b32_e32 v173, v172
	v_mov_b32_e32 v177, v176
	v_lshl_add_u64 v[178:179], v[166:167], 0, v[0:1]
	v_mov_b32_e32 v183, 0
	s_lshl_b32 s8, s101, 16
	s_sub_u32 s8, 0, s8
	s_subb_u32 s9, 0, 0
	s_waitcnt vmcnt(0)
	s_branch .LBB0_481
.LBB0_480:
	s_add_u32 s8, s8, 0xfffe0000
	v_cndmask_b32_e64 v0, v0, v17, s[2:3]
	v_cndmask_b32_e64 v183, v2, v19, s[2:3]
	s_addc_u32 s9, s9, -1
	s_cmpk_ge_i32 s12, 0x48
	v_fmac_f32_e32 v183, v0, v4
	ds_write_b32 v188, v183
	v_mov_b32_e32 v190, s12
	v_add_u32_e32 v190, -1, v190
	s_waitcnt lgkmcnt(0)
	ds_write_b32 v189, v190
	s_cbranch_scc1 .LBB0_483

; __device__ __forceinline__ unsigned short f2bf(float f) { return (unsigned short)(cvt_pk_bf16(f, 0.f) & 0xffffu); }
; template <int DIR>
; __device__ __forceinline__ void lru_item(const Params& p, int item, int lane) {
;     ...
;         float st = hst, hs[4];
; #pragma unroll
;         for (int Gi = 0; Gi < 8; ++Gi) {
;             const int q = Gi >> 1; const bool own = (hh == (Gi & 1));
;             const float A = own ? Ag[q] : Ap[q], B = own ? Bg[q] : Bp[q];
;             if (own) hs[q] = st;
;             st = A * st + B;
;         }
;         hst = st;
;         if (!is_ctx) {
;             bf16_t* yr = yl + ((size_t)bl * 2048 + tile * 32) * 1024 + d;
; #pragma unroll
;             for (int e = 0; e < 16; ++e) { const int k = DIR ? 15 - e : e; const float hv = av[k] * hs[k >> 2] + bv[k];
;                 const int tok = (e & 3) + 8 * (e >> 2) + 4 * h; yr[(size_t)tok * 1024] = f2bf(hv); }
.Llru_v1_spin:
	ds_read_b32 v190, v189
	s_waitcnt lgkmcnt(0)
	v_cmp_eq_u32_e32 vcc, s15, v190
	s_cbranch_vccnz .Llru_v1_go
	s_sleep 1
	s_branch .Llru_v1_spin
.Llru_v1_go:
	ds_read_b32 v183, v188
	s_waitcnt lgkmcnt(0)
	ds_bpermute_b32 v0, v180, v17
	ds_bpermute_b32 v2, v180, v19
	v_fmac_f32_e32 v6, v183, v10
	v_cndmask_b32_e64 v4, v4, v30, s[2:3]
	v_cndmask_b32_e64 v8, v8, v34, s[2:3]
	v_fmac_f32_e32 v8, v4, v6
	v_cndmask_b32_e64 v4, v31, v12, s[2:3]
	v_cndmask_b32_e64 v10, v35, v20, s[2:3]
	v_fmac_f32_e32 v10, v4, v8
	v_cndmask_b32_e64 v4, v12, v31, s[2:3]
	v_cndmask_b32_e64 v12, v20, v35, s[2:3]
	v_fmac_f32_e32 v12, v4, v10
	v_cndmask_b32_e64 v4, v16, v21, s[2:3]
	v_cndmask_b32_e64 v20, v18, v22, s[2:3]
	v_fmac_f32_e32 v20, v4, v12
	v_cndmask_b32_e64 v4, v21, v16, s[2:3]
	v_cndmask_b32_e64 v21, v22, v18, s[2:3]
	v_fmac_f32_e32 v21, v4, v20
	s_waitcnt lgkmcnt(1)
	v_cndmask_b32_e64 v22, v17, v0, s[2:3]
	s_waitcnt lgkmcnt(0)
	v_cndmask_b32_e64 v4, v19, v2, s[2:3]
	v_fmac_f32_e32 v4, v22, v21
	s_waitcnt vmcnt(0)
	s_cbranch_scc1 .LBB0_480
	v_cndmask_b32_e64 v22, v21, v4, s[2:3]
	v_cndmask_b32_e64 v12, v12, v20, s[2:3]
	v_lshl_add_u64 v[20:21], v[178:179], 0, s[8:9]
	s_mov_b32 s15, 0x1bd70000
	v_add_co_u32_e32 v32, vcc, s15, v20
	s_mov_b32 s15, 0x1bd71000
	s_nop 0
	v_addc_co_u32_e32 v33, vcc, 0, v21, vcc
	v_cndmask_b32_e64 v8, v8, v10, s[2:3]
	v_cndmask_b32_e64 v10, v183, v6, s[2:3]
	v_fma_f32 v6, v17, v22, v19
	v_add_co_u32_e32 v44, vcc, s15, v20
	v_cvt_pk_bf16_f32 v6, v6, v193
	s_mov_b32 s15, 0x1bd74000
	s_nop 0
	v_addc_co_u32_e32 v45, vcc, 0, v21, vcc
	global_store_short v[44:45], v6, off offset:-4096
	v_fma_f32 v6, v41, v22, v43
	v_cvt_pk_bf16_f32 v6, v6, v193
	global_store_short v[32:33], v6, off offset:2048
	v_fma_f32 v6, v37, v22, v39
	v_add_co_u32_e32 v32, vcc, s15, v20
	v_cvt_pk_bf16_f32 v6, v6, v193
	global_store_short v[44:45], v6, off
	v_fmac_f32_e32 v3, v1, v22
	v_cvt_pk_bf16_f32 v1, v3, v193
	v_addc_co_u32_e32 v33, vcc, 0, v21, vcc
	s_mov_b32 s15, 0x1bd75000
	global_store_short v[44:45], v1, off offset:2048
	v_fma_f32 v1, v16, v12, v18
	v_add_co_u32_e32 v44, vcc, s15, v20
	v_cvt_pk_bf16_f32 v1, v1, v193
	v_fmac_f32_e32 v42, v40, v12
	s_nop 0
	v_addc_co_u32_e32 v45, vcc, 0, v21, vcc
	global_store_short v[44:45], v1, off offset:-4096
	v_cvt_pk_bf16_f32 v1, v42, v193
	s_mov_b32 s15, 0x1bd78000
	global_store_short v[32:33], v1, off offset:2048
	v_fmac_f32_e32 v38, v36, v12
	v_cvt_pk_bf16_f32 v1, v38, v193
	v_fmac_f32_e32 v7, v5, v12
	v_add_co_u32_e32 v6, vcc, s15, v20
	global_store_short v[44:45], v1, off
	v_cvt_pk_bf16_f32 v1, v7, v193
	s_nop 0
	v_addc_co_u32_e32 v7, vcc, 0, v21, vcc
	s_mov_b32 s15, 0x1bd79000
	global_store_short v[44:45], v1, off offset:2048
	v_fma_f32 v1, v31, v8, v35
	v_add_co_u32_e32 v32, vcc, s15, v20
	v_cvt_pk_bf16_f32 v1, v1, v193
	v_fmac_f32_e32 v11, v9, v8
	s_nop 0
	v_addc_co_u32_e32 v33, vcc, 0, v21, vcc
	global_store_short v[32:33], v1, off offset:-4096
	v_fma_f32 v1, v27, v8, v29
	v_cvt_pk_bf16_f32 v1, v1, v193
	global_store_short v[6:7], v1, off offset:2048
	v_fma_f32 v1, v15, v8, v25
	v_cvt_pk_bf16_f32 v1, v1, v193
	global_store_short v[32:33], v1, off
	v_cvt_pk_bf16_f32 v1, v11, v193
	v_add_co_u32_e32 v6, vcc, 0x1bd7c000, v20
	global_store_short v[32:33], v1, off offset:2048
	v_fmac_f32_e32 v34, v30, v10
	v_cvt_pk_bf16_f32 v1, v34, v193
	v_addc_co_u32_e32 v7, vcc, 0, v21, vcc
	global_store_short v[6:7], v1, off
	v_fmac_f32_e32 v28, v26, v10
	v_cvt_pk_bf16_f32 v1, v28, v193
	global_store_short v[6:7], v1, off offset:2048
	v_add_co_u32_e32 v6, vcc, 0x1bd7d000, v20
	v_fmac_f32_e32 v24, v14, v10
	v_cvt_pk_bf16_f32 v1, v24, v193
	s_nop 0
	v_addc_co_u32_e32 v7, vcc, 0, v21, vcc
	global_store_short v[6:7], v1, off
	v_fmac_f32_e32 v13, v23, v10
	v_cvt_pk_bf16_f32 v1, v13, v193
	s_nop 1
	global_store_short v[6:7], v1, off offset:2048
	s_branch .LBB0_480

; __device__ __forceinline__ float log1p_small(float e) { return e < 0.03f ? e * (1.f - e * (0.5f - e * (0.33333334f - 0.25f * e))) : __logf(1.f + e); }
; __device__ __forceinline__ f32x16 mfma32(bf16x8 a, bf16x8 b, f32x16 c) { return __builtin_amdgcn_mfma_f32_32x32x16_bf16(a, b, c, 0, 0, 0); }
; template <int DIR>
; __device__ __forceinline__ void lru_item(const Params& p, int item, int lane) {
;     ...
;     const float c8 = -8.f * log1p_small(__expf(-p.lru_lambda[DIR * 1024 + d]));
;     const bf16_t* uu = (const bf16_t*)(p.ws + OFF_U);
;     bf16_t* yl = (bf16_t*)(p.ws + (DIR ? OFF_YLB : OFF_YLF));
;     float hst = 0.f;
;     auto tile_row0 = [&](int t) -> size_t { const bool cx = t < 8; const int tl = cx ? (DIR ? 7 - t : t) : (DIR ? 71 - t : t - 8);
;         return cx ? (size_t)bl * 256 + tl * 32 : (size_t)CGR + (size_t)bl * 2048 + tl * 32; };
;     bf16x8 uf[8], ui0, ui1;
;     { const bf16_t* up = uu + (tile_row0(0) + r) * 1024 + blk * 128 + 8 * h;
; #pragma unroll
;       for (int s = 0; s < 8; ++s) uf[s] = ld8(up + 16 * s);
;       ui0 = ld8(up + 32 * db); ui1 = ld8(up + 32 * db + 16); }
; #pragma unroll 1
;     for (int t = 0; t < 72; ++t) {
;         const bool is_ctx = t < 8;
;         const int tile = is_ctx ? (DIR ? 7 - t : t) : (DIR ? 71 - t : t - 8);
;         f32x16 Aa, Ai, Au;
; #pragma unroll
;         for (int e = 0; e < 16; ++e) { Aa[e] = 0.f; Ai[e] = 0.f; Au[e] = 0.f; }
; #pragma unroll
;         for (int s = 0; s < 8; ++s) { Aa = mfma32(uf[s], Wa[s], Aa); Ai = mfma32(uf[s], Wi[s], Ai); }
;         Au = mfma32(ui0, I0, Au); Au = mfma32(ui1, I1, Au);
;         { const int tn = t + 1 < 72 ? t + 1 : 71; const bf16_t* up = uu + (tile_row0(tn) + r) * 1024 + blk * 128 + 8 * h;
; #pragma unroll
;           for (int s = 0; s < 8; ++s) uf[s] = ld8(up + 16 * s);
;           ui0 = ld8(up + 32 * db); ui1 = ld8(up + 32 * db + 16); }
.LBB0_487:
	s_andn2_saveexec_b64 s[4:5], s[8:9]
	v_fmamk_f32 v0, v1, 0xbe800000, v237
	v_fma_f32 v0, -v1, v0, 0.5
	v_fma_f32 v0, -v1, v0, 1.0
	v_mul_f32_e32 v0, v1, v0
	s_or_b64 exec, exec, s[4:5]
	s_ashr_i32 s12, s11, 5
	s_ashr_i32 s13, s12, 31
	s_lshl_b64 s[4:5], s[12:13], 8
	v_mov_b32_e32 v3, s5
	v_or_b32_e32 v2, s4, v160
	v_lshlrev_b64 v[2:3], 11, v[2:3]
	v_lshl_add_u64 v[2:3], s[6:7], 0, v[2:3]
	s_lshl_b32 s8, s10, 1
	s_mov_b32 s9, s67
	v_lshl_add_u64 v[2:3], v[2:3], 0, s[8:9]
	v_lshl_add_u64 v[2:3], v[2:3], 0, v[192:193]
	s_lshl_b32 s100, s101, 16
	v_add_co_u32_e32 v2, vcc, s100, v2
	s_nop 1
	v_addc_co_u32_e32 v3, vcc, 0, v3, vcc
	global_load_dwordx4 v[152:155], v[2:3], off
	global_load_dwordx4 v[148:151], v[2:3], off offset:32
	global_load_dwordx4 v[144:147], v[2:3], off offset:64
	global_load_dwordx4 v[136:139], v[2:3], off offset:96
	global_load_dwordx4 v[132:135], v[2:3], off offset:128
	global_load_dwordx4 v[128:131], v[2:3], off offset:160
	global_load_dwordx4 v[124:127], v[2:3], off offset:192
	global_load_dwordx4 v[120:123], v[2:3], off offset:224
	v_lshl_add_u64 v[2:3], v[2:3], 0, s[66:67]
	global_load_dwordx4 v[156:159], v[2:3], off
	global_load_dwordx4 v[140:143], v[2:3], off offset:32
	v_mul_f32_e32 v0, 0xc1000000, v0
	s_lshl_b64 s[10:11], s[12:13], 22
	v_mul_f32_e32 v174, 0x3fb8aa3b, v0
	v_mov_b32_e32 v1, s11
	v_or_b32_e32 v0, s10, v182
	v_lshl_add_u64 v[172:173], v[164:165], 0, s[8:9]
	v_mov_b32_e32 v169, v168
	v_mov_b32_e32 v171, v170
	v_mov_b32_e32 v175, v174
	s_lshl_b64 s[8:9], s[12:13], 11
	v_lshl_add_u64 v[176:177], v[166:167], 0, v[0:1]
	s_mov_b32 s19, s101
	v_mov_b32_e32 v178, 0
	s_lshl_b32 s10, s101, 16
	s_mov_b32 s11, 0
	s_waitcnt vmcnt(0)
	s_branch .LBB0_491
.LBB0_490:
	s_add_u32 s10, s10, 0x20000
	v_cndmask_b32_e64 v0, v15, v1, s[2:3]
	v_cndmask_b32_e64 v178, v19, v3, s[2:3]
	s_addc_u32 s11, s11, 0
	v_fmac_f32_e32 v178, v0, v5
	ds_write_b32 v188, v178
	v_mov_b32_e32 v190, s18
	v_add_u32_e32 v190, -1, v190
	s_waitcnt lgkmcnt(0)
	ds_write_b32 v189, v190
	s_cmp_ge_u32 s10, 0x480000
	s_mov_b32 s19, s18
	s_cbranch_scc1 .LBB0_473

; __device__ __forceinline__ unsigned short f2bf(float f) { return (unsigned short)(cvt_pk_bf16(f, 0.f) & 0xffffu); }
; template <int DIR>
; __device__ __forceinline__ void lru_item(const Params& p, int item, int lane) {
;     ...
;         float st = hst, hs[4];
; #pragma unroll
;         for (int Gi = 0; Gi < 8; ++Gi) {
;             const int q = Gi >> 1; const bool own = (hh == (Gi & 1));
;             const float A = own ? Ag[q] : Ap[q], B = own ? Bg[q] : Bp[q];
;             if (own) hs[q] = st;
;             st = A * st + B;
;         }
;         hst = st;
;         if (!is_ctx) {
;             bf16_t* yr = yl + ((size_t)bl * 2048 + tile * 32) * 1024 + d;
; #pragma unroll
;             for (int e = 0; e < 16; ++e) { const int k = DIR ? 15 - e : e; const float hv = av[k] * hs[k >> 2] + bv[k];
;                 const int tok = (e & 3) + 8 * (e >> 2) + 4 * h; yr[(size_t)tok * 1024] = f2bf(hv); }
.Llru_v2_spin:
	ds_read_b32 v190, v189
	s_waitcnt lgkmcnt(0)
	v_cmp_eq_u32_e32 vcc, s19, v190
	s_cbranch_vccnz .Llru_v2_go
	s_sleep 1
	s_branch .Llru_v2_spin
.Llru_v2_go:
	ds_read_b32 v178, v188
	s_waitcnt lgkmcnt(0)
	ds_bpermute_b32 v1, v180, v15
	ds_bpermute_b32 v3, v180, v19
	v_fmac_f32_e32 v7, v178, v11
	v_cndmask_b32_e64 v5, v32, v5, s[2:3]
	v_cndmask_b32_e64 v9, v38, v9, s[2:3]
	v_fmac_f32_e32 v9, v5, v7
	v_cndmask_b32_e64 v5, v13, v33, s[2:3]
	v_cndmask_b32_e64 v11, v17, v39, s[2:3]
	v_fmac_f32_e32 v11, v5, v9
	v_cndmask_b32_e64 v5, v33, v13, s[2:3]
	v_cndmask_b32_e64 v13, v39, v17, s[2:3]
	v_fmac_f32_e32 v13, v5, v11
	v_cndmask_b32_e64 v5, v40, v14, s[2:3]
	v_cndmask_b32_e64 v17, v41, v18, s[2:3]
	v_fmac_f32_e32 v17, v5, v13
	v_cndmask_b32_e64 v5, v14, v40, s[2:3]
	v_cndmask_b32_e64 v40, v18, v41, s[2:3]
	v_fmac_f32_e32 v40, v5, v17
	s_waitcnt lgkmcnt(1)
	v_cndmask_b32_e64 v41, v1, v15, s[2:3]
	s_waitcnt lgkmcnt(0)
	v_cndmask_b32_e64 v5, v3, v19, s[2:3]
	s_cmp_lt_u32 s19, 8
	v_fmac_f32_e32 v5, v41, v40
	s_waitcnt vmcnt(0)
	s_cbranch_scc1 .LBB0_490
	v_cndmask_b32_e64 v7, v7, v178, s[2:3]
	v_cndmask_b32_e64 v13, v17, v13, s[2:3]
	v_fmac_f32_e32 v0, v16, v7
	v_lshl_add_u64 v[16:17], v[176:177], 0, s[10:11]
	s_mov_b32 s12, 0x17880000
	v_cndmask_b32_e64 v44, v5, v40, s[2:3]
	v_add_co_u32_e32 v40, vcc, s12, v16
	s_mov_b32 s12, 0x17881000
	s_nop 0
	v_addc_co_u32_e32 v41, vcc, 0, v17, vcc
	v_add_co_u32_e32 v42, vcc, s12, v16
	v_cvt_pk_bf16_f32 v0, v0, v193
	s_mov_b32 s12, 0x17884000
	s_nop 0
	v_addc_co_u32_e32 v43, vcc, 0, v17, vcc
	global_store_short v[42:43], v0, off offset:-4096
	v_fma_f32 v0, v28, v7, v30
	v_cvt_pk_bf16_f32 v0, v0, v193
	global_store_short v[40:41], v0, off offset:2048
	v_fma_f32 v0, v34, v7, v36
	v_cvt_pk_bf16_f32 v0, v0, v193
	v_add_co_u32_e32 v40, vcc, s12, v16
	global_store_short v[42:43], v0, off
	v_fma_f32 v0, v32, v7, v38
	v_addc_co_u32_e32 v41, vcc, 0, v17, vcc
	s_mov_b32 s12, 0x17885000
	v_cndmask_b32_e64 v9, v11, v9, s[2:3]
	v_cvt_pk_bf16_f32 v0, v0, v193
	global_store_short v[42:43], v0, off offset:2048
	v_add_co_u32_e32 v42, vcc, s12, v16
	v_fmac_f32_e32 v4, v2, v9
	v_cvt_pk_bf16_f32 v0, v4, v193
	s_nop 0
	v_addc_co_u32_e32 v43, vcc, 0, v17, vcc
	global_store_short v[42:43], v0, off offset:-4096
	v_fmac_f32_e32 v31, v29, v9
	v_cvt_pk_bf16_f32 v0, v31, v193
	s_mov_b32 s12, 0x17888000
	global_store_short v[40:41], v0, off offset:2048
	v_fmac_f32_e32 v37, v35, v9
	v_cvt_pk_bf16_f32 v0, v37, v193
	v_fmac_f32_e32 v8, v6, v13
	v_add_co_u32_e32 v6, vcc, s12, v16
	global_store_short v[42:43], v0, off
	v_fmac_f32_e32 v39, v33, v9
	v_cvt_pk_bf16_f32 v0, v39, v193
	v_addc_co_u32_e32 v7, vcc, 0, v17, vcc
	s_mov_b32 s12, 0x17889000
	global_store_short v[42:43], v0, off offset:2048
	v_cvt_pk_bf16_f32 v0, v8, v193
	v_add_co_u32_e32 v8, vcc, s12, v16
	v_fmac_f32_e32 v12, v10, v44
	s_nop 0
	v_addc_co_u32_e32 v9, vcc, 0, v17, vcc
	global_store_short v[8:9], v0, off offset:-4096
	v_fma_f32 v0, v20, v13, v22
	v_cvt_pk_bf16_f32 v0, v0, v193
	global_store_short v[6:7], v0, off offset:2048
	v_fma_f32 v0, v24, v13, v26
	v_cvt_pk_bf16_f32 v0, v0, v193
	global_store_short v[8:9], v0, off
	v_fma_f32 v0, v14, v13, v18
	v_cvt_pk_bf16_f32 v0, v0, v193
	v_add_co_u32_e32 v6, vcc, 0x1788c000, v16
	global_store_short v[8:9], v0, off offset:2048
	v_cvt_pk_bf16_f32 v0, v12, v193
	s_nop 0
	v_addc_co_u32_e32 v7, vcc, 0, v17, vcc
	global_store_short v[6:7], v0, off
	v_fmac_f32_e32 v23, v21, v44
	v_cvt_pk_bf16_f32 v0, v23, v193
	global_store_short v[6:7], v0, off offset:2048
	v_add_co_u32_e32 v6, vcc, 0x1788d000, v16
	v_fmac_f32_e32 v27, v25, v44
	v_cvt_pk_bf16_f32 v0, v27, v193
	s_nop 0
	v_addc_co_u32_e32 v7, vcc, 0, v17, vcc
	global_store_short v[6:7], v0, off
	v_fma_f32 v0, v15, v44, v19
	v_cvt_pk_bf16_f32 v0, v0, v193
	s_nop 1
	global_store_short v[6:7], v0, off offset:2048
	s_branch .LBB0_490
